# v12 + EpiP1 log path: drop denormal pre-scale and hi/lo ln2 product (v_log_f32 * ln2 in f32), 12 VALU -> 2 per element
# speedup vs baseline: 1.0041x; 1.0041x over previous
.LBB0_867:
	s_and_b64 vcc, exec, s[0:1]
	s_cbranch_vccz .LBB0_869
	v_mul_f32_e32 v144, 0xbfb8aa3b, v126
	v_exp_f32_e32 v144, v144
	v_sub_f32_e32 v143, 1.0, v175
	s_mov_b32 s0, 0x800000
	v_mul_f32_e32 v145, 0xbfb8aa3b, v122
	v_add_f32_e32 v144, 1.0, v144
	v_rcp_f32_e32 v144, v144
	v_exp_f32_e32 v145, v145
	s_mov_b32 s1, 0x3f317217
	s_mov_b32 s4, 0x7f800000
	v_fma_f32 v143, v144, v143, v175
	v_add_f32_e32 v145, 1.0, v145
	v_rcp_f32_e32 v145, v145
	v_log_f32_e32 v143, v143
	v_mul_f32_e32 v147, 0xbfb8aa3b, v123
	v_exp_f32_e32 v147, v147
	v_mul_f32_e32 v148, 0xbfb8aa3b, v128
	v_add_f32_e32 v147, 1.0, v147
	v_rcp_f32_e32 v147, v147
	v_mul_f32_e32 v144, 0x3f317217, v143
	v_sub_f32_e32 v143, 1.0, v174
	v_fma_f32 v143, v145, v143, v174
	v_exp_f32_e32 v148, v148
	v_mul_f32_e32 v149, 0xbfb8aa3b, v124
	v_log_f32_e32 v143, v143
	v_add_f32_e32 v148, 1.0, v148
	v_rcp_f32_e32 v148, v148
	v_exp_f32_e32 v149, v149
	s_nop 0
	v_add_f32_e32 v149, 1.0, v149
	v_rcp_f32_e32 v149, v149
	v_mul_f32_e32 v146, 0x3f317217, v143
	v_mul_f32_e32 v145, 0xbfb8aa3b, v127
	v_exp_f32_e32 v145, v145
	v_sub_f32_e32 v143, 1.0, v173
	v_mul_f32_e32 v151, 0xbfb8aa3b, v125
	v_exp_f32_e32 v151, v151
	v_add_f32_e32 v145, 1.0, v145
	v_rcp_f32_e32 v145, v145
	v_add_f32_e32 v151, 1.0, v151
	v_rcp_f32_e32 v151, v151
	v_fma_f32 v143, v145, v143, v173
	v_log_f32_e32 v143, v143
	s_nop 0
	v_mul_f32_e32 v145, 0x3f317217, v143
	v_sub_f32_e32 v143, 1.0, v172
	v_fma_f32 v143, v147, v143, v172
	v_log_f32_e32 v143, v143
	s_nop 0
	v_mul_f32_e32 v147, 0x3f317217, v143
	v_sub_f32_e32 v143, 1.0, v170
	v_fma_f32 v143, v148, v143, v170
	v_log_f32_e32 v143, v143
	s_nop 0
	v_mul_f32_e32 v148, 0x3f317217, v143
	v_sub_f32_e32 v143, 1.0, v168
	v_fma_f32 v143, v149, v143, v168
	v_log_f32_e32 v143, v143
	s_nop 0
	v_mul_f32_e32 v150, 0x3f317217, v143
	v_mul_f32_e32 v149, 0xbfb8aa3b, v129
	v_exp_f32_e32 v149, v149
	v_sub_f32_e32 v143, 1.0, v167
	v_add_f32_e32 v149, 1.0, v149
	v_rcp_f32_e32 v149, v149
	s_nop 0
	v_fma_f32 v143, v149, v143, v167
	v_log_f32_e32 v143, v143
	s_nop 0
	v_mul_f32_e32 v149, 0x3f317217, v143
	v_sub_f32_e32 v143, 1.0, v141
	v_fma_f32 v143, v151, v143, v141
	v_log_f32_e32 v143, v143
	s_nop 0
	v_mul_f32_e32 v151, 0x3f317217, v143

.LBB0_881:
	s_and_b64 vcc, exec, s[0:1]
	s_cbranch_vccz .LBB0_883
	v_mul_f32_e32 v125, 0xbfb8aa3b, v118
	v_exp_f32_e32 v125, v125
	v_sub_f32_e32 v124, 1.0, v175
	s_mov_b32 s0, 0x800000
	v_mul_f32_e32 v126, 0xbfb8aa3b, v114
	v_add_f32_e32 v125, 1.0, v125
	v_rcp_f32_e32 v125, v125
	v_exp_f32_e32 v126, v126
	s_mov_b32 s1, 0x3f317217
	s_mov_b32 s4, 0x7f800000
	v_fma_f32 v124, v125, v124, v175
	v_add_f32_e32 v126, 1.0, v126
	v_rcp_f32_e32 v126, v126
	v_log_f32_e32 v124, v124
	v_mul_f32_e32 v127, 0xbfb8aa3b, v119
	v_exp_f32_e32 v127, v127
	v_mul_f32_e32 v128, 0xbfb8aa3b, v115
	v_add_f32_e32 v127, 1.0, v127
	v_rcp_f32_e32 v127, v127
	v_mul_f32_e32 v124, 0x3f317217, v124
	v_sub_f32_e32 v125, 1.0, v174
	v_fma_f32 v125, v126, v125, v174
	v_exp_f32_e32 v128, v128
	v_mul_f32_e32 v129, 0xbfb8aa3b, v120
	v_log_f32_e32 v125, v125
	v_add_f32_e32 v128, 1.0, v128
	v_rcp_f32_e32 v128, v128
	v_exp_f32_e32 v129, v129
	s_nop 0
	v_add_f32_e32 v129, 1.0, v129
	v_rcp_f32_e32 v129, v129
	v_mul_f32_e32 v126, 0x3f317217, v125
	v_sub_f32_e32 v125, 1.0, v173
	v_fma_f32 v125, v127, v125, v173
	v_mul_f32_e32 v144, 0xbfb8aa3b, v116
	v_exp_f32_e32 v144, v144
	v_log_f32_e32 v125, v125
	v_add_f32_e32 v144, 1.0, v144
	v_rcp_f32_e32 v144, v144
	v_mul_f32_e32 v145, 0xbfb8aa3b, v121
	v_exp_f32_e32 v145, v145
	v_mul_f32_e32 v146, 0xbfb8aa3b, v117
	v_mul_f32_e32 v125, 0x3f317217, v125
	v_sub_f32_e32 v127, 1.0, v172
	v_fma_f32 v127, v128, v127, v172
	v_add_f32_e32 v145, 1.0, v145
	v_rcp_f32_e32 v145, v145
	v_log_f32_e32 v127, v127
	v_exp_f32_e32 v146, v146
	s_nop 0
	v_add_f32_e32 v146, 1.0, v146
	v_rcp_f32_e32 v146, v146
	v_mul_f32_e32 v127, 0x3f317217, v127
	v_sub_f32_e32 v128, 1.0, v170
	v_fma_f32 v128, v129, v128, v170
	v_log_f32_e32 v128, v128
	s_nop 0
	v_mul_f32_e32 v128, 0x3f317217, v128
	v_sub_f32_e32 v129, 1.0, v168
	v_fma_f32 v129, v144, v129, v168
	v_log_f32_e32 v129, v129
	s_nop 0
	v_mul_f32_e32 v144, 0x3f317217, v129
	v_sub_f32_e32 v129, 1.0, v167
	v_fma_f32 v129, v145, v129, v167
	v_log_f32_e32 v129, v129
	s_nop 0
	v_mul_f32_e32 v129, 0x3f317217, v129
	v_sub_f32_e32 v145, 1.0, v141
	v_fma_f32 v145, v146, v145, v141
	v_log_f32_e32 v145, v145
	s_nop 0
	v_mul_f32_e32 v145, 0x3f317217, v145

.LBB0_895:
	s_and_b64 vcc, exec, s[0:1]
	s_cbranch_vccz .LBB0_897
	v_mul_f32_e32 v117, 0xbfb8aa3b, v110
	v_exp_f32_e32 v117, v117
	v_sub_f32_e32 v116, 1.0, v175
	s_mov_b32 s0, 0x800000
	v_mul_f32_e32 v118, 0xbfb8aa3b, v106
	v_add_f32_e32 v117, 1.0, v117
	v_rcp_f32_e32 v117, v117
	v_exp_f32_e32 v118, v118
	s_mov_b32 s1, 0x3f317217
	s_mov_b32 s4, 0x7f800000
	v_fma_f32 v116, v117, v116, v175
	v_add_f32_e32 v118, 1.0, v118
	v_rcp_f32_e32 v118, v118
	v_log_f32_e32 v116, v116
	v_mul_f32_e32 v119, 0xbfb8aa3b, v111
	v_exp_f32_e32 v119, v119
	v_mul_f32_e32 v120, 0xbfb8aa3b, v107
	v_add_f32_e32 v119, 1.0, v119
	v_rcp_f32_e32 v119, v119
	v_mul_f32_e32 v116, 0x3f317217, v116
	v_sub_f32_e32 v117, 1.0, v174
	v_fma_f32 v117, v118, v117, v174
	v_exp_f32_e32 v120, v120
	v_mul_f32_e32 v121, 0xbfb8aa3b, v112
	v_log_f32_e32 v117, v117
	v_add_f32_e32 v120, 1.0, v120
	v_rcp_f32_e32 v120, v120
	v_exp_f32_e32 v121, v121
	s_nop 0
	v_add_f32_e32 v121, 1.0, v121
	v_rcp_f32_e32 v121, v121
	v_mul_f32_e32 v118, 0x3f317217, v117
	v_sub_f32_e32 v117, 1.0, v173
	v_fma_f32 v117, v119, v117, v173
	v_mul_f32_e32 v124, 0xbfb8aa3b, v108
	v_exp_f32_e32 v124, v124
	v_log_f32_e32 v117, v117
	v_add_f32_e32 v124, 1.0, v124
	v_rcp_f32_e32 v124, v124
	v_mul_f32_e32 v125, 0xbfb8aa3b, v113
	v_exp_f32_e32 v125, v125
	v_mul_f32_e32 v126, 0xbfb8aa3b, v109
	v_mul_f32_e32 v117, 0x3f317217, v117
	v_sub_f32_e32 v119, 1.0, v172
	v_fma_f32 v119, v120, v119, v172
	v_add_f32_e32 v125, 1.0, v125
	v_rcp_f32_e32 v125, v125
	v_log_f32_e32 v119, v119
	v_exp_f32_e32 v126, v126
	s_nop 0
	v_add_f32_e32 v126, 1.0, v126
	v_rcp_f32_e32 v126, v126
	v_mul_f32_e32 v119, 0x3f317217, v119
	v_sub_f32_e32 v120, 1.0, v170
	v_fma_f32 v120, v121, v120, v170
	v_log_f32_e32 v120, v120
	s_nop 0
	v_mul_f32_e32 v120, 0x3f317217, v120
	v_sub_f32_e32 v121, 1.0, v168
	v_fma_f32 v121, v124, v121, v168
	v_log_f32_e32 v121, v121
	s_nop 0
	v_mul_f32_e32 v124, 0x3f317217, v121
	v_sub_f32_e32 v121, 1.0, v167
	v_fma_f32 v121, v125, v121, v167
	v_log_f32_e32 v121, v121
	s_nop 0
	v_mul_f32_e32 v121, 0x3f317217, v121
	v_sub_f32_e32 v125, 1.0, v141
	v_fma_f32 v125, v126, v125, v141
	v_log_f32_e32 v125, v125
	s_nop 0
	v_mul_f32_e32 v125, 0x3f317217, v125

.LBB0_909:
	s_and_b64 vcc, exec, s[0:1]
	s_cbranch_vccz .LBB0_911
	v_mul_f32_e32 v109, 0xbfb8aa3b, v102
	v_exp_f32_e32 v109, v109
	v_sub_f32_e32 v108, 1.0, v175
	s_mov_b32 s0, 0x800000
	v_mul_f32_e32 v110, 0xbfb8aa3b, v98
	v_add_f32_e32 v109, 1.0, v109
	v_rcp_f32_e32 v109, v109
	v_exp_f32_e32 v110, v110
	s_mov_b32 s1, 0x3f317217
	s_mov_b32 s4, 0x7f800000
	v_fma_f32 v108, v109, v108, v175
	v_add_f32_e32 v110, 1.0, v110
	v_rcp_f32_e32 v110, v110
	v_log_f32_e32 v108, v108
	v_mul_f32_e32 v111, 0xbfb8aa3b, v103
	v_exp_f32_e32 v111, v111
	v_mul_f32_e32 v112, 0xbfb8aa3b, v99
	v_add_f32_e32 v111, 1.0, v111
	v_rcp_f32_e32 v111, v111
	v_mul_f32_e32 v108, 0x3f317217, v108
	v_sub_f32_e32 v109, 1.0, v174
	v_fma_f32 v109, v110, v109, v174
	v_exp_f32_e32 v112, v112
	v_mul_f32_e32 v113, 0xbfb8aa3b, v104
	v_log_f32_e32 v109, v109
	v_add_f32_e32 v112, 1.0, v112
	v_rcp_f32_e32 v112, v112
	v_exp_f32_e32 v113, v113
	s_nop 0
	v_add_f32_e32 v113, 1.0, v113
	v_rcp_f32_e32 v113, v113
	v_mul_f32_e32 v110, 0x3f317217, v109
	v_sub_f32_e32 v109, 1.0, v173
	v_fma_f32 v109, v111, v109, v173
	v_mul_f32_e32 v116, 0xbfb8aa3b, v100
	v_exp_f32_e32 v116, v116
	v_log_f32_e32 v109, v109
	v_add_f32_e32 v116, 1.0, v116
	v_rcp_f32_e32 v116, v116
	v_mul_f32_e32 v117, 0xbfb8aa3b, v105
	v_exp_f32_e32 v117, v117
	v_mul_f32_e32 v118, 0xbfb8aa3b, v101
	v_mul_f32_e32 v109, 0x3f317217, v109
	v_sub_f32_e32 v111, 1.0, v172
	v_fma_f32 v111, v112, v111, v172
	v_add_f32_e32 v117, 1.0, v117
	v_rcp_f32_e32 v117, v117
	v_log_f32_e32 v111, v111
	v_exp_f32_e32 v118, v118
	s_nop 0
	v_add_f32_e32 v118, 1.0, v118
	v_rcp_f32_e32 v118, v118
	v_mul_f32_e32 v111, 0x3f317217, v111
	v_sub_f32_e32 v112, 1.0, v170
	v_fma_f32 v112, v113, v112, v170
	v_log_f32_e32 v112, v112
	s_nop 0
	v_mul_f32_e32 v112, 0x3f317217, v112
	v_sub_f32_e32 v113, 1.0, v168
	v_fma_f32 v113, v116, v113, v168
	v_log_f32_e32 v113, v113
	s_nop 0
	v_mul_f32_e32 v116, 0x3f317217, v113
	v_sub_f32_e32 v113, 1.0, v167
	v_fma_f32 v113, v117, v113, v167
	v_log_f32_e32 v113, v113
	s_nop 0
	v_mul_f32_e32 v113, 0x3f317217, v113
	v_sub_f32_e32 v117, 1.0, v141
	v_fma_f32 v117, v118, v117, v141
	v_log_f32_e32 v117, v117
	s_nop 0
	v_mul_f32_e32 v117, 0x3f317217, v117

.LBB0_923:
	s_and_b64 vcc, exec, s[0:1]
	s_cbranch_vccz .LBB0_925
	v_mul_f32_e32 v101, 0xbfb8aa3b, v94
	v_exp_f32_e32 v101, v101
	v_sub_f32_e32 v100, 1.0, v175
	s_mov_b32 s0, 0x800000
	v_mul_f32_e32 v102, 0xbfb8aa3b, v90
	v_add_f32_e32 v101, 1.0, v101
	v_rcp_f32_e32 v101, v101
	v_exp_f32_e32 v102, v102
	s_mov_b32 s1, 0x3f317217
	s_mov_b32 s4, 0x7f800000
	v_fma_f32 v100, v101, v100, v175
	v_add_f32_e32 v102, 1.0, v102
	v_rcp_f32_e32 v102, v102
	v_log_f32_e32 v100, v100
	v_mul_f32_e32 v103, 0xbfb8aa3b, v95
	v_exp_f32_e32 v103, v103
	v_mul_f32_e32 v104, 0xbfb8aa3b, v91
	v_add_f32_e32 v103, 1.0, v103
	v_rcp_f32_e32 v103, v103
	v_mul_f32_e32 v100, 0x3f317217, v100
	v_sub_f32_e32 v101, 1.0, v174
	v_fma_f32 v101, v102, v101, v174
	v_exp_f32_e32 v104, v104
	v_mul_f32_e32 v105, 0xbfb8aa3b, v96
	v_log_f32_e32 v101, v101
	v_add_f32_e32 v104, 1.0, v104
	v_rcp_f32_e32 v104, v104
	v_exp_f32_e32 v105, v105
	s_nop 0
	v_add_f32_e32 v105, 1.0, v105
	v_rcp_f32_e32 v105, v105
	v_mul_f32_e32 v102, 0x3f317217, v101
	v_sub_f32_e32 v101, 1.0, v173
	v_fma_f32 v101, v103, v101, v173
	v_mul_f32_e32 v108, 0xbfb8aa3b, v92
	v_exp_f32_e32 v108, v108
	v_log_f32_e32 v101, v101
	v_add_f32_e32 v108, 1.0, v108
	v_rcp_f32_e32 v108, v108
	v_mul_f32_e32 v109, 0xbfb8aa3b, v97
	v_exp_f32_e32 v109, v109
	v_mul_f32_e32 v110, 0xbfb8aa3b, v93
	v_mul_f32_e32 v101, 0x3f317217, v101
	v_sub_f32_e32 v103, 1.0, v172
	v_fma_f32 v103, v104, v103, v172
	v_add_f32_e32 v109, 1.0, v109
	v_rcp_f32_e32 v109, v109
	v_log_f32_e32 v103, v103
	v_exp_f32_e32 v110, v110
	s_nop 0
	v_add_f32_e32 v110, 1.0, v110
	v_rcp_f32_e32 v110, v110
	v_mul_f32_e32 v103, 0x3f317217, v103
	v_sub_f32_e32 v104, 1.0, v170
	v_fma_f32 v104, v105, v104, v170
	v_log_f32_e32 v104, v104
	s_nop 0
	v_mul_f32_e32 v104, 0x3f317217, v104
	v_sub_f32_e32 v105, 1.0, v168
	v_fma_f32 v105, v108, v105, v168
	v_log_f32_e32 v105, v105
	s_nop 0
	v_mul_f32_e32 v108, 0x3f317217, v105
	v_sub_f32_e32 v105, 1.0, v167
	v_fma_f32 v105, v109, v105, v167
	v_log_f32_e32 v105, v105
	s_nop 0
	v_mul_f32_e32 v105, 0x3f317217, v105
	v_sub_f32_e32 v109, 1.0, v141
	v_fma_f32 v109, v110, v109, v141
	v_log_f32_e32 v109, v109
	s_nop 0
	v_mul_f32_e32 v109, 0x3f317217, v109

.LBB0_937:
	s_and_b64 vcc, exec, s[0:1]
	s_cbranch_vccz .LBB0_939
	v_mul_f32_e32 v93, 0xbfb8aa3b, v86
	v_exp_f32_e32 v93, v93
	v_sub_f32_e32 v92, 1.0, v175
	s_mov_b32 s0, 0x800000
	v_mul_f32_e32 v94, 0xbfb8aa3b, v82
	v_add_f32_e32 v93, 1.0, v93
	v_rcp_f32_e32 v93, v93
	v_exp_f32_e32 v94, v94
	s_mov_b32 s1, 0x3f317217
	s_mov_b32 s4, 0x7f800000
	v_fma_f32 v92, v93, v92, v175
	v_add_f32_e32 v94, 1.0, v94
	v_rcp_f32_e32 v94, v94
	v_log_f32_e32 v92, v92
	v_mul_f32_e32 v95, 0xbfb8aa3b, v87
	v_exp_f32_e32 v95, v95
	v_mul_f32_e32 v96, 0xbfb8aa3b, v83
	v_add_f32_e32 v95, 1.0, v95
	v_rcp_f32_e32 v95, v95
	v_mul_f32_e32 v92, 0x3f317217, v92
	v_sub_f32_e32 v93, 1.0, v174
	v_fma_f32 v93, v94, v93, v174
	v_exp_f32_e32 v96, v96
	v_mul_f32_e32 v97, 0xbfb8aa3b, v88
	v_log_f32_e32 v93, v93
	v_add_f32_e32 v96, 1.0, v96
	v_rcp_f32_e32 v96, v96
	v_exp_f32_e32 v97, v97
	s_nop 0
	v_add_f32_e32 v97, 1.0, v97
	v_rcp_f32_e32 v97, v97
	v_mul_f32_e32 v94, 0x3f317217, v93
	v_sub_f32_e32 v93, 1.0, v173
	v_fma_f32 v93, v95, v93, v173
	v_mul_f32_e32 v100, 0xbfb8aa3b, v84
	v_exp_f32_e32 v100, v100
	v_log_f32_e32 v93, v93
	v_add_f32_e32 v100, 1.0, v100
	v_rcp_f32_e32 v100, v100
	v_mul_f32_e32 v101, 0xbfb8aa3b, v89
	v_exp_f32_e32 v101, v101
	v_mul_f32_e32 v102, 0xbfb8aa3b, v85
	v_mul_f32_e32 v93, 0x3f317217, v93
	v_sub_f32_e32 v95, 1.0, v172
	v_fma_f32 v95, v96, v95, v172
	v_add_f32_e32 v101, 1.0, v101
	v_rcp_f32_e32 v101, v101
	v_log_f32_e32 v95, v95
	v_exp_f32_e32 v102, v102
	s_nop 0
	v_add_f32_e32 v102, 1.0, v102
	v_rcp_f32_e32 v102, v102
	v_mul_f32_e32 v95, 0x3f317217, v95
	v_sub_f32_e32 v96, 1.0, v170
	v_fma_f32 v96, v97, v96, v170
	v_log_f32_e32 v96, v96
	s_nop 0
	v_mul_f32_e32 v96, 0x3f317217, v96
	v_sub_f32_e32 v97, 1.0, v168
	v_fma_f32 v97, v100, v97, v168
	v_log_f32_e32 v97, v97
	s_nop 0
	v_mul_f32_e32 v100, 0x3f317217, v97
	v_sub_f32_e32 v97, 1.0, v167
	v_fma_f32 v97, v101, v97, v167
	v_log_f32_e32 v97, v97
	s_nop 0
	v_mul_f32_e32 v97, 0x3f317217, v97
	v_sub_f32_e32 v101, 1.0, v141
	v_fma_f32 v101, v102, v101, v141
	v_log_f32_e32 v101, v101
	s_nop 0
	v_mul_f32_e32 v101, 0x3f317217, v101

.LBB0_951:
	s_and_b64 vcc, exec, s[0:1]
	s_cbranch_vccz .LBB0_953
	v_mul_f32_e32 v85, 0xbfb8aa3b, v78
	v_exp_f32_e32 v85, v85
	v_sub_f32_e32 v84, 1.0, v175
	s_mov_b32 s0, 0x800000
	v_mul_f32_e32 v86, 0xbfb8aa3b, v74
	v_add_f32_e32 v85, 1.0, v85
	v_rcp_f32_e32 v85, v85
	v_exp_f32_e32 v86, v86
	s_mov_b32 s1, 0x3f317217
	s_mov_b32 s4, 0x7f800000
	v_fma_f32 v84, v85, v84, v175
	v_add_f32_e32 v86, 1.0, v86
	v_rcp_f32_e32 v86, v86
	v_log_f32_e32 v84, v84
	v_mul_f32_e32 v87, 0xbfb8aa3b, v79
	v_exp_f32_e32 v87, v87
	v_mul_f32_e32 v88, 0xbfb8aa3b, v75
	v_add_f32_e32 v87, 1.0, v87
	v_rcp_f32_e32 v87, v87
	v_mul_f32_e32 v84, 0x3f317217, v84
	v_sub_f32_e32 v85, 1.0, v174
	v_fma_f32 v85, v86, v85, v174
	v_exp_f32_e32 v88, v88
	v_mul_f32_e32 v89, 0xbfb8aa3b, v80
	v_log_f32_e32 v85, v85
	v_add_f32_e32 v88, 1.0, v88
	v_rcp_f32_e32 v88, v88
	v_exp_f32_e32 v89, v89
	s_nop 0
	v_add_f32_e32 v89, 1.0, v89
	v_rcp_f32_e32 v89, v89
	v_mul_f32_e32 v86, 0x3f317217, v85
	v_sub_f32_e32 v85, 1.0, v173
	v_fma_f32 v85, v87, v85, v173
	v_mul_f32_e32 v92, 0xbfb8aa3b, v76
	v_exp_f32_e32 v92, v92
	v_log_f32_e32 v85, v85
	v_add_f32_e32 v92, 1.0, v92
	v_rcp_f32_e32 v92, v92
	v_mul_f32_e32 v93, 0xbfb8aa3b, v81
	v_exp_f32_e32 v93, v93
	v_mul_f32_e32 v94, 0xbfb8aa3b, v77
	v_mul_f32_e32 v85, 0x3f317217, v85
	v_sub_f32_e32 v87, 1.0, v172
	v_fma_f32 v87, v88, v87, v172
	v_add_f32_e32 v93, 1.0, v93
	v_rcp_f32_e32 v93, v93
	v_log_f32_e32 v87, v87
	v_exp_f32_e32 v94, v94
	s_nop 0
	v_add_f32_e32 v94, 1.0, v94
	v_rcp_f32_e32 v94, v94
	v_mul_f32_e32 v87, 0x3f317217, v87
	v_sub_f32_e32 v88, 1.0, v170
	v_fma_f32 v88, v89, v88, v170
	v_log_f32_e32 v88, v88
	s_nop 0
	v_mul_f32_e32 v88, 0x3f317217, v88
	v_sub_f32_e32 v89, 1.0, v168
	v_fma_f32 v89, v92, v89, v168
	v_log_f32_e32 v89, v89
	s_nop 0
	v_mul_f32_e32 v92, 0x3f317217, v89
	v_sub_f32_e32 v89, 1.0, v167
	v_fma_f32 v89, v93, v89, v167
	v_log_f32_e32 v89, v89
	s_nop 0
	v_mul_f32_e32 v89, 0x3f317217, v89
	v_sub_f32_e32 v93, 1.0, v141
	v_fma_f32 v93, v94, v93, v141
	v_log_f32_e32 v93, v93
	s_nop 0
	v_mul_f32_e32 v93, 0x3f317217, v93

.LBB0_965:
	s_and_b64 vcc, exec, s[0:1]
	s_cbranch_vccz .LBB0_967
	v_mul_f32_e32 v77, 0xbfb8aa3b, v70
	v_exp_f32_e32 v77, v77
	v_sub_f32_e32 v76, 1.0, v175
	s_mov_b32 s0, 0x800000
	v_mul_f32_e32 v78, 0xbfb8aa3b, v66
	v_add_f32_e32 v77, 1.0, v77
	v_rcp_f32_e32 v77, v77
	v_exp_f32_e32 v78, v78
	s_mov_b32 s1, 0x3f317217
	s_mov_b32 s4, 0x7f800000
	v_fma_f32 v76, v77, v76, v175
	v_add_f32_e32 v78, 1.0, v78
	v_rcp_f32_e32 v78, v78
	v_log_f32_e32 v76, v76
	v_mul_f32_e32 v79, 0xbfb8aa3b, v71
	v_exp_f32_e32 v79, v79
	v_mul_f32_e32 v80, 0xbfb8aa3b, v67
	v_add_f32_e32 v79, 1.0, v79
	v_rcp_f32_e32 v79, v79
	v_mul_f32_e32 v76, 0x3f317217, v76
	v_sub_f32_e32 v77, 1.0, v174
	v_fma_f32 v77, v78, v77, v174
	v_exp_f32_e32 v80, v80
	v_mul_f32_e32 v81, 0xbfb8aa3b, v72
	v_log_f32_e32 v77, v77
	v_add_f32_e32 v80, 1.0, v80
	v_rcp_f32_e32 v80, v80
	v_exp_f32_e32 v81, v81
	s_nop 0
	v_add_f32_e32 v81, 1.0, v81
	v_rcp_f32_e32 v81, v81
	v_mul_f32_e32 v78, 0x3f317217, v77
	v_sub_f32_e32 v77, 1.0, v173
	v_fma_f32 v77, v79, v77, v173
	v_mul_f32_e32 v84, 0xbfb8aa3b, v68
	v_exp_f32_e32 v84, v84
	v_log_f32_e32 v77, v77
	v_add_f32_e32 v84, 1.0, v84
	v_rcp_f32_e32 v84, v84
	v_mul_f32_e32 v85, 0xbfb8aa3b, v73
	v_exp_f32_e32 v85, v85
	v_mul_f32_e32 v86, 0xbfb8aa3b, v69
	v_mul_f32_e32 v77, 0x3f317217, v77
	v_sub_f32_e32 v79, 1.0, v172
	v_fma_f32 v79, v80, v79, v172
	v_add_f32_e32 v85, 1.0, v85
	v_rcp_f32_e32 v85, v85
	v_log_f32_e32 v79, v79
	v_exp_f32_e32 v86, v86
	s_nop 0
	v_add_f32_e32 v86, 1.0, v86
	v_rcp_f32_e32 v86, v86
	v_mul_f32_e32 v79, 0x3f317217, v79
	v_sub_f32_e32 v80, 1.0, v170
	v_fma_f32 v80, v81, v80, v170
	v_log_f32_e32 v80, v80
	s_nop 0
	v_mul_f32_e32 v80, 0x3f317217, v80
	v_sub_f32_e32 v81, 1.0, v168
	v_fma_f32 v81, v84, v81, v168
	v_log_f32_e32 v81, v81
	s_nop 0
	v_mul_f32_e32 v84, 0x3f317217, v81
	v_sub_f32_e32 v81, 1.0, v167
	v_fma_f32 v81, v85, v81, v167
	v_log_f32_e32 v81, v81
	s_nop 0
	v_mul_f32_e32 v81, 0x3f317217, v81
	v_sub_f32_e32 v85, 1.0, v141
	v_fma_f32 v85, v86, v85, v141
	v_log_f32_e32 v85, v85
	s_nop 0
	v_mul_f32_e32 v85, 0x3f317217, v85

.LBB0_981:
	s_and_b64 vcc, exec, s[0:1]
	s_cbranch_vccz .LBB0_983
	v_mul_f32_e32 v69, 0xbfb8aa3b, v62
	v_exp_f32_e32 v69, v69
	v_sub_f32_e32 v68, 1.0, v175
	s_mov_b32 s0, 0x800000
	v_mul_f32_e32 v70, 0xbfb8aa3b, v58
	v_add_f32_e32 v69, 1.0, v69
	v_rcp_f32_e32 v69, v69
	v_exp_f32_e32 v70, v70
	s_mov_b32 s1, 0x3f317217
	s_mov_b32 s2, 0x7f800000
	v_fma_f32 v68, v69, v68, v175
	v_add_f32_e32 v70, 1.0, v70
	v_rcp_f32_e32 v70, v70
	v_log_f32_e32 v68, v68
	v_mul_f32_e32 v71, 0xbfb8aa3b, v63
	v_exp_f32_e32 v71, v71
	v_mul_f32_e32 v72, 0xbfb8aa3b, v59
	v_add_f32_e32 v71, 1.0, v71
	v_rcp_f32_e32 v71, v71
	v_mul_f32_e32 v68, 0x3f317217, v68
	v_sub_f32_e32 v69, 1.0, v174
	v_fma_f32 v69, v70, v69, v174
	v_exp_f32_e32 v72, v72
	v_mul_f32_e32 v73, 0xbfb8aa3b, v64
	v_log_f32_e32 v69, v69
	v_add_f32_e32 v72, 1.0, v72
	v_rcp_f32_e32 v72, v72
	v_exp_f32_e32 v73, v73
	s_nop 0
	v_add_f32_e32 v73, 1.0, v73
	v_rcp_f32_e32 v73, v73
	v_mul_f32_e32 v70, 0x3f317217, v69
	v_sub_f32_e32 v69, 1.0, v173
	v_fma_f32 v69, v71, v69, v173
	v_mul_f32_e32 v76, 0xbfb8aa3b, v60
	v_exp_f32_e32 v76, v76
	v_log_f32_e32 v69, v69
	v_add_f32_e32 v76, 1.0, v76
	v_rcp_f32_e32 v76, v76
	v_mul_f32_e32 v77, 0xbfb8aa3b, v65
	v_exp_f32_e32 v77, v77
	v_mul_f32_e32 v78, 0xbfb8aa3b, v61
	v_mul_f32_e32 v69, 0x3f317217, v69
	v_sub_f32_e32 v71, 1.0, v172
	v_fma_f32 v71, v72, v71, v172
	v_add_f32_e32 v77, 1.0, v77
	v_rcp_f32_e32 v77, v77
	v_log_f32_e32 v71, v71
	v_exp_f32_e32 v78, v78
	s_nop 0
	v_add_f32_e32 v78, 1.0, v78
	v_rcp_f32_e32 v78, v78
	v_mul_f32_e32 v71, 0x3f317217, v71
	v_sub_f32_e32 v72, 1.0, v170
	v_fma_f32 v72, v73, v72, v170
	v_log_f32_e32 v72, v72
	s_nop 0
	v_mul_f32_e32 v72, 0x3f317217, v72
	v_sub_f32_e32 v73, 1.0, v168
	v_fma_f32 v73, v76, v73, v168
	v_log_f32_e32 v73, v73
	s_nop 0
	v_mul_f32_e32 v76, 0x3f317217, v73
	v_sub_f32_e32 v73, 1.0, v167
	v_fma_f32 v73, v77, v73, v167
	v_log_f32_e32 v73, v73
	s_nop 0
	v_mul_f32_e32 v73, 0x3f317217, v73
	v_sub_f32_e32 v77, 1.0, v141
	v_fma_f32 v77, v78, v77, v141
	v_log_f32_e32 v77, v77
	s_nop 0
	v_mul_f32_e32 v77, 0x3f317217, v77

.LBB0_995:
	s_and_b64 vcc, exec, s[0:1]
	s_cbranch_vccz .LBB0_997
	v_mul_f32_e32 v59, 0xbfb8aa3b, v54
	v_exp_f32_e32 v59, v59
	v_sub_f32_e32 v58, 1.0, v175
	s_mov_b32 s0, 0x800000
	v_mul_f32_e32 v60, 0xbfb8aa3b, v50
	v_add_f32_e32 v59, 1.0, v59
	v_rcp_f32_e32 v59, v59
	v_exp_f32_e32 v60, v60
	s_mov_b32 s1, 0x3f317217
	s_mov_b32 s2, 0x7f800000
	v_fma_f32 v58, v59, v58, v175
	v_add_f32_e32 v60, 1.0, v60
	v_rcp_f32_e32 v60, v60
	v_log_f32_e32 v58, v58
	v_mul_f32_e32 v61, 0xbfb8aa3b, v55
	v_exp_f32_e32 v61, v61
	v_mul_f32_e32 v62, 0xbfb8aa3b, v51
	v_add_f32_e32 v61, 1.0, v61
	v_rcp_f32_e32 v61, v61
	v_mul_f32_e32 v58, 0x3f317217, v58
	v_sub_f32_e32 v59, 1.0, v174
	v_fma_f32 v59, v60, v59, v174
	v_exp_f32_e32 v62, v62
	v_mul_f32_e32 v63, 0xbfb8aa3b, v56
	v_log_f32_e32 v59, v59
	v_add_f32_e32 v62, 1.0, v62
	v_rcp_f32_e32 v62, v62
	v_exp_f32_e32 v63, v63
	s_nop 0
	v_add_f32_e32 v63, 1.0, v63
	v_rcp_f32_e32 v63, v63
	v_mul_f32_e32 v60, 0x3f317217, v59
	v_sub_f32_e32 v59, 1.0, v173
	v_fma_f32 v59, v61, v59, v173
	v_mul_f32_e32 v64, 0xbfb8aa3b, v52
	v_exp_f32_e32 v64, v64
	v_log_f32_e32 v59, v59
	v_add_f32_e32 v64, 1.0, v64
	v_rcp_f32_e32 v64, v64
	v_mul_f32_e32 v65, 0xbfb8aa3b, v57
	v_exp_f32_e32 v65, v65
	v_mul_f32_e32 v68, 0xbfb8aa3b, v53
	v_mul_f32_e32 v59, 0x3f317217, v59
	v_sub_f32_e32 v61, 1.0, v172
	v_fma_f32 v61, v62, v61, v172
	v_add_f32_e32 v65, 1.0, v65
	v_rcp_f32_e32 v65, v65
	v_log_f32_e32 v61, v61
	v_exp_f32_e32 v68, v68
	s_nop 0
	v_add_f32_e32 v68, 1.0, v68
	v_rcp_f32_e32 v68, v68
	v_mul_f32_e32 v61, 0x3f317217, v61
	v_sub_f32_e32 v62, 1.0, v170
	v_fma_f32 v62, v63, v62, v170
	v_log_f32_e32 v62, v62
	s_nop 0
	v_mul_f32_e32 v62, 0x3f317217, v62
	v_sub_f32_e32 v63, 1.0, v168
	v_fma_f32 v63, v64, v63, v168
	v_log_f32_e32 v63, v63
	s_nop 0
	v_mul_f32_e32 v64, 0x3f317217, v63
	v_sub_f32_e32 v63, 1.0, v167
	v_fma_f32 v63, v65, v63, v167
	v_log_f32_e32 v63, v63
	s_nop 0
	v_mul_f32_e32 v63, 0x3f317217, v63
	v_sub_f32_e32 v65, 1.0, v141
	v_fma_f32 v65, v68, v65, v141
	v_log_f32_e32 v65, v65
	s_nop 0
	v_mul_f32_e32 v65, 0x3f317217, v65

.LBB0_1009:
	s_and_b64 vcc, exec, s[0:1]
	s_cbranch_vccz .LBB0_1011
	v_mul_f32_e32 v51, 0xbfb8aa3b, v46
	v_exp_f32_e32 v51, v51
	v_sub_f32_e32 v50, 1.0, v175
	s_mov_b32 s0, 0x800000
	v_mul_f32_e32 v52, 0xbfb8aa3b, v42
	v_add_f32_e32 v51, 1.0, v51
	v_rcp_f32_e32 v51, v51
	v_exp_f32_e32 v52, v52
	s_mov_b32 s1, 0x3f317217
	s_mov_b32 s2, 0x7f800000
	v_fma_f32 v50, v51, v50, v175
	v_add_f32_e32 v52, 1.0, v52
	v_rcp_f32_e32 v52, v52
	v_log_f32_e32 v50, v50
	v_mul_f32_e32 v53, 0xbfb8aa3b, v47
	v_exp_f32_e32 v53, v53
	v_mul_f32_e32 v54, 0xbfb8aa3b, v43
	v_add_f32_e32 v53, 1.0, v53
	v_rcp_f32_e32 v53, v53
	v_mul_f32_e32 v50, 0x3f317217, v50
	v_sub_f32_e32 v51, 1.0, v174
	v_fma_f32 v51, v52, v51, v174
	v_exp_f32_e32 v54, v54
	v_mul_f32_e32 v55, 0xbfb8aa3b, v48
	v_log_f32_e32 v51, v51
	v_add_f32_e32 v54, 1.0, v54
	v_rcp_f32_e32 v54, v54
	v_exp_f32_e32 v55, v55
	s_nop 0
	v_add_f32_e32 v55, 1.0, v55
	v_rcp_f32_e32 v55, v55
	v_mul_f32_e32 v52, 0x3f317217, v51
	v_sub_f32_e32 v51, 1.0, v173
	v_fma_f32 v51, v53, v51, v173
	v_mul_f32_e32 v56, 0xbfb8aa3b, v44
	v_exp_f32_e32 v56, v56
	v_log_f32_e32 v51, v51
	v_add_f32_e32 v56, 1.0, v56
	v_rcp_f32_e32 v56, v56
	v_mul_f32_e32 v57, 0xbfb8aa3b, v49
	v_exp_f32_e32 v57, v57
	v_mul_f32_e32 v58, 0xbfb8aa3b, v45
	v_mul_f32_e32 v51, 0x3f317217, v51
	v_sub_f32_e32 v53, 1.0, v172
	v_fma_f32 v53, v54, v53, v172
	v_add_f32_e32 v57, 1.0, v57
	v_rcp_f32_e32 v57, v57
	v_log_f32_e32 v53, v53
	v_exp_f32_e32 v58, v58
	s_nop 0
	v_add_f32_e32 v58, 1.0, v58
	v_rcp_f32_e32 v58, v58
	v_mul_f32_e32 v53, 0x3f317217, v53
	v_sub_f32_e32 v54, 1.0, v170
	v_fma_f32 v54, v55, v54, v170
	v_log_f32_e32 v54, v54
	s_nop 0
	v_mul_f32_e32 v54, 0x3f317217, v54
	v_sub_f32_e32 v55, 1.0, v168
	v_fma_f32 v55, v56, v55, v168
	v_log_f32_e32 v55, v55
	s_nop 0
	v_mul_f32_e32 v56, 0x3f317217, v55
	v_sub_f32_e32 v55, 1.0, v167
	v_fma_f32 v55, v57, v55, v167
	v_log_f32_e32 v55, v55
	s_nop 0
	v_mul_f32_e32 v55, 0x3f317217, v55
	v_sub_f32_e32 v57, 1.0, v141
	v_fma_f32 v57, v58, v57, v141
	v_log_f32_e32 v57, v57
	s_nop 0
	v_mul_f32_e32 v57, 0x3f317217, v57

.LBB0_1023:
	s_and_b64 vcc, exec, s[0:1]
	s_cbranch_vccz .LBB0_1025
	v_mul_f32_e32 v43, 0xbfb8aa3b, v38
	v_exp_f32_e32 v43, v43
	v_sub_f32_e32 v42, 1.0, v175
	s_mov_b32 s0, 0x800000
	v_mul_f32_e32 v44, 0xbfb8aa3b, v34
	v_add_f32_e32 v43, 1.0, v43
	v_rcp_f32_e32 v43, v43
	v_exp_f32_e32 v44, v44
	s_mov_b32 s1, 0x3f317217
	s_mov_b32 s2, 0x7f800000
	v_fma_f32 v42, v43, v42, v175
	v_add_f32_e32 v44, 1.0, v44
	v_rcp_f32_e32 v44, v44
	v_log_f32_e32 v42, v42
	v_mul_f32_e32 v45, 0xbfb8aa3b, v39
	v_exp_f32_e32 v45, v45
	v_mul_f32_e32 v46, 0xbfb8aa3b, v35
	v_add_f32_e32 v45, 1.0, v45
	v_rcp_f32_e32 v45, v45
	v_mul_f32_e32 v42, 0x3f317217, v42
	v_sub_f32_e32 v43, 1.0, v174
	v_fma_f32 v43, v44, v43, v174
	v_exp_f32_e32 v46, v46
	v_mul_f32_e32 v47, 0xbfb8aa3b, v40
	v_log_f32_e32 v43, v43
	v_add_f32_e32 v46, 1.0, v46
	v_rcp_f32_e32 v46, v46
	v_exp_f32_e32 v47, v47
	s_nop 0
	v_add_f32_e32 v47, 1.0, v47
	v_rcp_f32_e32 v47, v47
	v_mul_f32_e32 v44, 0x3f317217, v43
	v_sub_f32_e32 v43, 1.0, v173
	v_fma_f32 v43, v45, v43, v173
	v_mul_f32_e32 v48, 0xbfb8aa3b, v36
	v_exp_f32_e32 v48, v48
	v_log_f32_e32 v43, v43
	v_add_f32_e32 v48, 1.0, v48
	v_rcp_f32_e32 v48, v48
	v_mul_f32_e32 v49, 0xbfb8aa3b, v41
	v_exp_f32_e32 v49, v49
	v_mul_f32_e32 v50, 0xbfb8aa3b, v37
	v_mul_f32_e32 v43, 0x3f317217, v43
	v_sub_f32_e32 v45, 1.0, v172
	v_fma_f32 v45, v46, v45, v172
	v_add_f32_e32 v49, 1.0, v49
	v_rcp_f32_e32 v49, v49
	v_log_f32_e32 v45, v45
	v_exp_f32_e32 v50, v50
	s_nop 0
	v_add_f32_e32 v50, 1.0, v50
	v_rcp_f32_e32 v50, v50
	v_mul_f32_e32 v45, 0x3f317217, v45
	v_sub_f32_e32 v46, 1.0, v170
	v_fma_f32 v46, v47, v46, v170
	v_log_f32_e32 v46, v46
	s_nop 0
	v_mul_f32_e32 v46, 0x3f317217, v46
	v_sub_f32_e32 v47, 1.0, v168
	v_fma_f32 v47, v48, v47, v168
	v_log_f32_e32 v47, v47
	s_nop 0
	v_mul_f32_e32 v48, 0x3f317217, v47
	v_sub_f32_e32 v47, 1.0, v167
	v_fma_f32 v47, v49, v47, v167
	v_log_f32_e32 v47, v47
	s_nop 0
	v_mul_f32_e32 v47, 0x3f317217, v47
	v_sub_f32_e32 v49, 1.0, v141
	v_fma_f32 v49, v50, v49, v141
	v_log_f32_e32 v49, v49
	s_nop 0
	v_mul_f32_e32 v49, 0x3f317217, v49

.LBB0_1037:
	s_and_b64 vcc, exec, s[0:1]
	s_cbranch_vccz .LBB0_1039
	v_mul_f32_e32 v35, 0xbfb8aa3b, v30
	v_exp_f32_e32 v35, v35
	v_sub_f32_e32 v34, 1.0, v175
	s_mov_b32 s0, 0x800000
	v_mul_f32_e32 v36, 0xbfb8aa3b, v26
	v_add_f32_e32 v35, 1.0, v35
	v_rcp_f32_e32 v35, v35
	v_exp_f32_e32 v36, v36
	s_mov_b32 s1, 0x3f317217
	s_mov_b32 s2, 0x7f800000
	v_fma_f32 v34, v35, v34, v175
	v_add_f32_e32 v36, 1.0, v36
	v_rcp_f32_e32 v36, v36
	v_log_f32_e32 v34, v34
	v_mul_f32_e32 v37, 0xbfb8aa3b, v31
	v_exp_f32_e32 v37, v37
	v_mul_f32_e32 v38, 0xbfb8aa3b, v27
	v_add_f32_e32 v37, 1.0, v37
	v_rcp_f32_e32 v37, v37
	v_mul_f32_e32 v34, 0x3f317217, v34
	v_sub_f32_e32 v35, 1.0, v174
	v_fma_f32 v35, v36, v35, v174
	v_exp_f32_e32 v38, v38
	v_mul_f32_e32 v39, 0xbfb8aa3b, v32
	v_log_f32_e32 v35, v35
	v_add_f32_e32 v38, 1.0, v38
	v_rcp_f32_e32 v38, v38
	v_exp_f32_e32 v39, v39
	s_nop 0
	v_add_f32_e32 v39, 1.0, v39
	v_rcp_f32_e32 v39, v39
	v_mul_f32_e32 v36, 0x3f317217, v35
	v_sub_f32_e32 v35, 1.0, v173
	v_fma_f32 v35, v37, v35, v173
	v_mul_f32_e32 v40, 0xbfb8aa3b, v28
	v_exp_f32_e32 v40, v40
	v_log_f32_e32 v35, v35
	v_add_f32_e32 v40, 1.0, v40
	v_rcp_f32_e32 v40, v40
	v_mul_f32_e32 v41, 0xbfb8aa3b, v33
	v_exp_f32_e32 v41, v41
	v_mul_f32_e32 v42, 0xbfb8aa3b, v29
	v_mul_f32_e32 v35, 0x3f317217, v35
	v_sub_f32_e32 v37, 1.0, v172
	v_fma_f32 v37, v38, v37, v172
	v_add_f32_e32 v41, 1.0, v41
	v_rcp_f32_e32 v41, v41
	v_log_f32_e32 v37, v37
	v_exp_f32_e32 v42, v42
	s_nop 0
	v_add_f32_e32 v42, 1.0, v42
	v_rcp_f32_e32 v42, v42
	v_mul_f32_e32 v37, 0x3f317217, v37
	v_sub_f32_e32 v38, 1.0, v170
	v_fma_f32 v38, v39, v38, v170
	v_log_f32_e32 v38, v38
	s_nop 0
	v_mul_f32_e32 v38, 0x3f317217, v38
	v_sub_f32_e32 v39, 1.0, v168
	v_fma_f32 v39, v40, v39, v168
	v_log_f32_e32 v39, v39
	s_nop 0
	v_mul_f32_e32 v40, 0x3f317217, v39
	v_sub_f32_e32 v39, 1.0, v167
	v_fma_f32 v39, v41, v39, v167
	v_log_f32_e32 v39, v39
	s_nop 0
	v_mul_f32_e32 v39, 0x3f317217, v39
	v_sub_f32_e32 v41, 1.0, v141
	v_fma_f32 v41, v42, v41, v141
	v_log_f32_e32 v41, v41
	s_nop 0
	v_mul_f32_e32 v41, 0x3f317217, v41

.LBB0_1051:
	s_and_b64 vcc, exec, s[0:1]
	s_cbranch_vccz .LBB0_1053
	v_mul_f32_e32 v27, 0xbfb8aa3b, v22
	v_exp_f32_e32 v27, v27
	v_sub_f32_e32 v26, 1.0, v175
	s_mov_b32 s0, 0x800000
	v_mul_f32_e32 v28, 0xbfb8aa3b, v18
	v_add_f32_e32 v27, 1.0, v27
	v_rcp_f32_e32 v27, v27
	v_exp_f32_e32 v28, v28
	s_mov_b32 s1, 0x3f317217
	s_mov_b32 s2, 0x7f800000
	v_fma_f32 v26, v27, v26, v175
	v_add_f32_e32 v28, 1.0, v28
	v_rcp_f32_e32 v28, v28
	v_log_f32_e32 v26, v26
	v_mul_f32_e32 v29, 0xbfb8aa3b, v23
	v_exp_f32_e32 v29, v29
	v_mul_f32_e32 v30, 0xbfb8aa3b, v19
	v_add_f32_e32 v29, 1.0, v29
	v_rcp_f32_e32 v29, v29
	v_mul_f32_e32 v26, 0x3f317217, v26
	v_sub_f32_e32 v27, 1.0, v174
	v_fma_f32 v27, v28, v27, v174
	v_exp_f32_e32 v30, v30
	v_mul_f32_e32 v31, 0xbfb8aa3b, v24
	v_log_f32_e32 v27, v27
	v_add_f32_e32 v30, 1.0, v30
	v_rcp_f32_e32 v30, v30
	v_exp_f32_e32 v31, v31
	s_nop 0
	v_add_f32_e32 v31, 1.0, v31
	v_rcp_f32_e32 v31, v31
	v_mul_f32_e32 v28, 0x3f317217, v27
	v_sub_f32_e32 v27, 1.0, v173
	v_fma_f32 v27, v29, v27, v173
	v_mul_f32_e32 v32, 0xbfb8aa3b, v20
	v_exp_f32_e32 v32, v32
	v_log_f32_e32 v27, v27
	v_add_f32_e32 v32, 1.0, v32
	v_rcp_f32_e32 v32, v32
	v_mul_f32_e32 v33, 0xbfb8aa3b, v25
	v_exp_f32_e32 v33, v33
	v_mul_f32_e32 v34, 0xbfb8aa3b, v21
	v_mul_f32_e32 v27, 0x3f317217, v27
	v_sub_f32_e32 v29, 1.0, v172
	v_fma_f32 v29, v30, v29, v172
	v_add_f32_e32 v33, 1.0, v33
	v_rcp_f32_e32 v33, v33
	v_log_f32_e32 v29, v29
	v_exp_f32_e32 v34, v34
	s_nop 0
	v_add_f32_e32 v34, 1.0, v34
	v_rcp_f32_e32 v34, v34
	v_mul_f32_e32 v29, 0x3f317217, v29
	v_sub_f32_e32 v30, 1.0, v170
	v_fma_f32 v30, v31, v30, v170
	v_log_f32_e32 v30, v30
	s_nop 0
	v_mul_f32_e32 v30, 0x3f317217, v30
	v_sub_f32_e32 v31, 1.0, v168
	v_fma_f32 v31, v32, v31, v168
	v_log_f32_e32 v31, v31
	s_nop 0
	v_mul_f32_e32 v32, 0x3f317217, v31
	v_sub_f32_e32 v31, 1.0, v167
	v_fma_f32 v31, v33, v31, v167
	v_log_f32_e32 v31, v31
	s_nop 0
	v_mul_f32_e32 v31, 0x3f317217, v31
	v_sub_f32_e32 v33, 1.0, v141
	v_fma_f32 v33, v34, v33, v141
	v_log_f32_e32 v33, v33
	s_nop 0
	v_mul_f32_e32 v33, 0x3f317217, v33

.LBB0_1065:
	s_and_b64 vcc, exec, s[0:1]
	s_cbranch_vccz .LBB0_1067
	v_mul_f32_e32 v19, 0xbfb8aa3b, v14
	v_exp_f32_e32 v19, v19
	v_sub_f32_e32 v18, 1.0, v175
	s_mov_b32 s0, 0x800000
	v_mul_f32_e32 v20, 0xbfb8aa3b, v10
	v_add_f32_e32 v19, 1.0, v19
	v_rcp_f32_e32 v19, v19
	v_exp_f32_e32 v20, v20
	s_mov_b32 s1, 0x3f317217
	s_mov_b32 s2, 0x7f800000
	v_fma_f32 v18, v19, v18, v175
	v_add_f32_e32 v20, 1.0, v20
	v_rcp_f32_e32 v20, v20
	v_log_f32_e32 v18, v18
	v_mul_f32_e32 v21, 0xbfb8aa3b, v15
	v_exp_f32_e32 v21, v21
	v_mul_f32_e32 v22, 0xbfb8aa3b, v11
	v_add_f32_e32 v21, 1.0, v21
	v_rcp_f32_e32 v21, v21
	v_mul_f32_e32 v18, 0x3f317217, v18
	v_sub_f32_e32 v19, 1.0, v174
	v_fma_f32 v19, v20, v19, v174
	v_exp_f32_e32 v22, v22
	v_mul_f32_e32 v23, 0xbfb8aa3b, v16
	v_log_f32_e32 v19, v19
	v_add_f32_e32 v22, 1.0, v22
	v_rcp_f32_e32 v22, v22
	v_exp_f32_e32 v23, v23
	s_nop 0
	v_add_f32_e32 v23, 1.0, v23
	v_rcp_f32_e32 v23, v23
	v_mul_f32_e32 v20, 0x3f317217, v19
	v_sub_f32_e32 v19, 1.0, v173
	v_fma_f32 v19, v21, v19, v173
	v_mul_f32_e32 v24, 0xbfb8aa3b, v12
	v_exp_f32_e32 v24, v24
	v_log_f32_e32 v19, v19
	v_add_f32_e32 v24, 1.0, v24
	v_rcp_f32_e32 v24, v24
	v_mul_f32_e32 v25, 0xbfb8aa3b, v17
	v_exp_f32_e32 v25, v25
	v_mul_f32_e32 v26, 0xbfb8aa3b, v13
	v_mul_f32_e32 v19, 0x3f317217, v19
	v_sub_f32_e32 v21, 1.0, v172
	v_fma_f32 v21, v22, v21, v172
	v_add_f32_e32 v25, 1.0, v25
	v_rcp_f32_e32 v25, v25
	v_log_f32_e32 v21, v21
	v_exp_f32_e32 v26, v26
	s_nop 0
	v_add_f32_e32 v26, 1.0, v26
	v_rcp_f32_e32 v26, v26
	v_mul_f32_e32 v21, 0x3f317217, v21
	v_sub_f32_e32 v22, 1.0, v170
	v_fma_f32 v22, v23, v22, v170
	v_log_f32_e32 v22, v22
	s_nop 0
	v_mul_f32_e32 v22, 0x3f317217, v22
	v_sub_f32_e32 v23, 1.0, v168
	v_fma_f32 v23, v24, v23, v168
	v_log_f32_e32 v23, v23
	s_nop 0
	v_mul_f32_e32 v24, 0x3f317217, v23
	v_sub_f32_e32 v23, 1.0, v167
	v_fma_f32 v23, v25, v23, v167
	v_log_f32_e32 v23, v23
	s_nop 0
	v_mul_f32_e32 v23, 0x3f317217, v23
	v_sub_f32_e32 v25, 1.0, v141
	v_fma_f32 v25, v26, v25, v141
	v_log_f32_e32 v25, v25
	s_nop 0
	v_mul_f32_e32 v25, 0x3f317217, v25

.LBB0_1079:
	s_and_b64 vcc, exec, s[0:1]
	s_cbranch_vccz .LBB0_1081
	v_mul_f32_e32 v11, 0xbfb8aa3b, v6
	v_exp_f32_e32 v11, v11
	v_sub_f32_e32 v10, 1.0, v175
	s_mov_b32 s0, 0x800000
	v_mul_f32_e32 v12, 0xbfb8aa3b, v0
	v_add_f32_e32 v11, 1.0, v11
	v_rcp_f32_e32 v11, v11
	v_exp_f32_e32 v12, v12
	s_mov_b32 s1, 0x3f317217
	s_mov_b32 s2, 0x7f800000
	v_fmac_f32_e32 v175, v11, v10
	v_add_f32_e32 v12, 1.0, v12
	v_rcp_f32_e32 v12, v12
	v_log_f32_e32 v10, v175
	v_mul_f32_e32 v13, 0xbfb8aa3b, v7
	v_exp_f32_e32 v13, v13
	v_mul_f32_e32 v14, 0xbfb8aa3b, v1
	v_add_f32_e32 v13, 1.0, v13
	v_rcp_f32_e32 v13, v13
	v_mul_f32_e32 v10, 0x3f317217, v10
	v_sub_f32_e32 v11, 1.0, v174
	v_fmac_f32_e32 v174, v12, v11
	v_exp_f32_e32 v14, v14
	v_mul_f32_e32 v15, 0xbfb8aa3b, v8
	v_log_f32_e32 v11, v174
	v_add_f32_e32 v14, 1.0, v14
	v_rcp_f32_e32 v14, v14
	v_exp_f32_e32 v15, v15
	s_nop 0
	v_add_f32_e32 v15, 1.0, v15
	v_rcp_f32_e32 v15, v15
	v_mul_f32_e32 v12, 0x3f317217, v11
	v_sub_f32_e32 v11, 1.0, v173
	v_fmac_f32_e32 v173, v13, v11
	v_mul_f32_e32 v16, 0xbfb8aa3b, v2
	v_exp_f32_e32 v16, v16
	v_log_f32_e32 v11, v173
	v_add_f32_e32 v16, 1.0, v16
	v_rcp_f32_e32 v16, v16
	v_mul_f32_e32 v17, 0xbfb8aa3b, v9
	v_exp_f32_e32 v17, v17
	v_mul_f32_e32 v18, 0xbfb8aa3b, v3
	v_mul_f32_e32 v11, 0x3f317217, v11
	v_sub_f32_e32 v13, 1.0, v172
	v_fmac_f32_e32 v172, v14, v13
	v_add_f32_e32 v17, 1.0, v17
	v_rcp_f32_e32 v17, v17
	v_log_f32_e32 v13, v172
	v_exp_f32_e32 v18, v18
	s_nop 0
	v_add_f32_e32 v18, 1.0, v18
	v_rcp_f32_e32 v18, v18
	v_mul_f32_e32 v13, 0x3f317217, v13
	v_sub_f32_e32 v14, 1.0, v170
	v_fmac_f32_e32 v170, v15, v14
	v_log_f32_e32 v14, v170
	s_nop 0
	v_mul_f32_e32 v14, 0x3f317217, v14
	v_sub_f32_e32 v15, 1.0, v168
	v_fmac_f32_e32 v168, v16, v15
	v_log_f32_e32 v15, v168
	s_nop 0
	v_mul_f32_e32 v16, 0x3f317217, v15
	v_sub_f32_e32 v15, 1.0, v167
	v_fmac_f32_e32 v167, v17, v15
	v_log_f32_e32 v15, v167
	s_nop 0
	v_mul_f32_e32 v15, 0x3f317217, v15
	v_sub_f32_e32 v17, 1.0, v141
	v_fmac_f32_e32 v141, v18, v17
	v_log_f32_e32 v17, v141
	s_nop 0
	v_mul_f32_e32 v17, 0x3f317217, v17
